# panel-local seams use a 4-workgroup (row-panel group) barrier instead of the XCC-wide one; ALiBi term in the attention loop with abs/neg fma modifiers (fewer VALU ops)
# speedup vs baseline: 1.0172x; 1.0172x over previous
; __device__ __forceinline__ void attn_unit(LAS unsigned char* lds, const bf16* PROJ, bf16* DA, const float* sinkl, int unit, int tid, int wid, int lane) {
;     ...
;             const float fb = fb0 - (float)(32 * i);
;             const int sb0 = s0 + c0 + 4 * hi;
;             const float kmin = fmaxf(fb - 128.0f, (float)(-sb0)), kmax = fminf(fb + 128.0f, (float)(SEQ - 1 - sb0));
;             const float kmid = 0.5f * (kmin + kmax), khw = 0.5f * (kmax - kmin);
;             float mx = NEG;
; #pragma unroll
;             for (int r = 0; r < 16; ++r) { const float kr = (float)((r & 3) + 8 * (r >> 2)); p[r] = p[r] - slope2 * fabsf(fb - kr); }
.LBB0_382:
	v_add_u32_e32 v105, s23, v95
	v_add_u32_e32 v104, 0x80, v105
	v_cvt_f32_i32_e32 v104, v104
	s_and_b32 s25, s24, 7
	s_cmp_eq_u32 s25, 0
	v_fma_f32 v50, -v162, |v104|, v50
	v_subrev_f32_e32 v106, 0x3f800000, v104
	v_fma_f32 v51, -v163, |v106|, v51
	v_subrev_f32_e32 v107, 0x40000000, v104
	v_fma_f32 v52, -v162, |v107|, v52
	v_subrev_f32_e32 v106, 0x40400000, v104
	v_fma_f32 v53, -v163, |v106|, v53
	v_subrev_f32_e32 v107, 0x41000000, v104
	v_fma_f32 v54, -v162, |v107|, v54
	v_subrev_f32_e32 v106, 0x41100000, v104
	v_fma_f32 v55, -v163, |v106|, v55
	v_subrev_f32_e32 v107, 0x41200000, v104
	v_fma_f32 v56, -v162, |v107|, v56
	v_subrev_f32_e32 v106, 0x41300000, v104
	v_fma_f32 v57, -v163, |v106|, v57
	v_subrev_f32_e32 v107, 0x41800000, v104
	v_fma_f32 v58, -v162, |v107|, v58
	v_subrev_f32_e32 v106, 0x41880000, v104
	v_fma_f32 v59, -v163, |v106|, v59
	v_subrev_f32_e32 v107, 0x41900000, v104
	v_fma_f32 v60, -v162, |v107|, v60
	v_subrev_f32_e32 v106, 0x41980000, v104
	v_fma_f32 v61, -v163, |v106|, v61
	v_subrev_f32_e32 v107, 0x41c00000, v104
	v_fma_f32 v62, -v162, |v107|, v62
	v_subrev_f32_e32 v106, 0x41c80000, v104
	v_fma_f32 v63, -v163, |v106|, v63
	v_subrev_f32_e32 v107, 0x41d00000, v104
	v_fma_f32 v64, -v162, |v107|, v64
	v_subrev_f32_e32 v106, 0x41d80000, v104
	v_fma_f32 v65, -v163, |v106|, v65
	s_cbranch_scc1 .LBB0_391
	s_cmp_gt_i32 s78, 30
	s_mov_b64 s[38:39], -1
	s_cbranch_scc1 .LBB0_385
	s_cmp_eq_u32 s78, 0
	s_cselect_b64 s[38:39], -1, 0

; __device__ __forceinline__ unsigned xb_ld(unsigned* p)              { return __hip_atomic_load(p, __ATOMIC_RELAXED, __HIP_MEMORY_SCOPE_AGENT); }
; __device__ __forceinline__ unsigned xb_add(unsigned* p, unsigned v) { return __hip_atomic_fetch_add(p, v, __ATOMIC_RELAXED, __HIP_MEMORY_SCOPE_AGENT); }
; #define XB_SPIN(cond, bar) do { unsigned _sp = 0; while (cond) { __builtin_amdgcn_s_sleep(1); \
;     if ((++_sp & 255u) == 0u) { if (xb_ld(&(bar)[XB_TMO])) break; if (_sp > XB_SPIN_CAP) { atomicAdd(&(bar)[XB_TMO], 1u); break; } } } } while (0)
; __device__ __forceinline__ void xcc_local_barrier(unsigned* bar2, unsigned x, unsigned nloc, unsigned* tmobar) {
;     asm volatile("s_waitcnt vmcnt(0)" ::: "memory");
;     __syncthreads();
;     if (threadIdx.x == 0) {
;         const unsigned old = xb_add(&bar2[XB_XSUB(x)], 1u);
;         const unsigned gen = old / nloc;
;         if (old + 1u == (gen + 1u) * nloc) (void)xb_add(&bar2[XB_XGEN(x)], 1u);
;         else XB_SPIN(xb_ld(&bar2[XB_XGEN(x)]) == gen, tmobar);
;         __builtin_amdgcn_fence(__ATOMIC_ACQUIRE, "agent");
;         asm volatile("s_waitcnt vmcnt(0)" ::: "memory");
;     }
;     __syncthreads();
; }
.LBB0_478:
	s_and_b64 vcc, exec, s[38:39]
	s_cbranch_vccz .LBB0_498
	v_readlane_b32 s6, v238, 25
	s_nop 1
	v_mov_b32_e32 v2, s6
	ds_read_b32 v2, v2
	s_waitcnt vmcnt(0)
	v_readlane_b32 s6, v242, 38
	v_readlane_b32 s7, v242, 39
	s_waitcnt vmcnt(0) lgkmcnt(0)
	s_barrier
	s_and_saveexec_b64 s[38:39], s[6:7]
	s_cbranch_execz .LBB0_497
	v_readlane_b32 s6, v239, 63
	v_readlane_b32 s7, v241, 0
	v_mov_b32_e32 v3, 1
	s_nop 4
	global_atomic_add v4, v66, v3, s[6:7] offset:128 sc0
	buffer_inv sc1
	s_waitcnt vmcnt(0)
	v_readfirstlane_b32 s98, v4
	s_nop 3
	s_lshr_b32 s99, s98, 2
	s_and_b32 s98, s98, 3
	s_cmp_eq_u32 s98, 3
	s_cbranch_scc1 .Lgrp_last_0
	s_mov_b32 s100, 0
.Lgrp_poll_0:
	global_load_dword v3, v66, s[6:7] offset:192 sc1
	s_waitcnt vmcnt(0)
	v_readfirstlane_b32 s98, v3
	s_nop 3
	s_cmp_lg_u32 s98, s99
	s_cbranch_scc1 .Lgrp_done_0
	s_sleep 1
	s_add_i32 s100, s100, 1
	s_cmp_lt_u32 s100, 0x10000
	s_cbranch_scc1 .Lgrp_poll_0
	s_branch .Lgrp_done_0
.Lgrp_last_0:
	v_mov_b32_e32 v3, 1
	global_atomic_add v66, v3, s[6:7] offset:192
.Lgrp_done_0:
	s_waitcnt vmcnt(0)
.LBB0_497:
	s_or_b64 exec, exec, s[38:39]
	s_barrier

; __device__ __forceinline__ unsigned xb_ld(unsigned* p)              { return __hip_atomic_load(p, __ATOMIC_RELAXED, __HIP_MEMORY_SCOPE_AGENT); }
; __device__ __forceinline__ unsigned xb_add(unsigned* p, unsigned v) { return __hip_atomic_fetch_add(p, v, __ATOMIC_RELAXED, __HIP_MEMORY_SCOPE_AGENT); }
; #define XB_SPIN(cond, bar) do { unsigned _sp = 0; while (cond) { __builtin_amdgcn_s_sleep(1); \
;     if ((++_sp & 255u) == 0u) { if (xb_ld(&(bar)[XB_TMO])) break; if (_sp > XB_SPIN_CAP) { atomicAdd(&(bar)[XB_TMO], 1u); break; } } } } while (0)
; __device__ __forceinline__ void xcc_local_barrier(unsigned* bar2, unsigned x, unsigned nloc, unsigned* tmobar) {
;     asm volatile("s_waitcnt vmcnt(0)" ::: "memory");
;     __syncthreads();
;     if (threadIdx.x == 0) {
;         const unsigned old = xb_add(&bar2[XB_XSUB(x)], 1u);
;         const unsigned gen = old / nloc;
;         if (old + 1u == (gen + 1u) * nloc) (void)xb_add(&bar2[XB_XGEN(x)], 1u);
;         else XB_SPIN(xb_ld(&bar2[XB_XGEN(x)]) == gen, tmobar);
.LBB0_612:
	s_and_b64 vcc, exec, s[40:41]
	s_cbranch_vccz .LBB0_632
	v_readlane_b32 s6, v238, 25
	s_nop 1
	v_mov_b32_e32 v2, s6
	ds_read_b32 v2, v2
	s_waitcnt vmcnt(0)
	v_readlane_b32 s6, v242, 38
	v_readlane_b32 s7, v242, 39
	s_waitcnt vmcnt(0) lgkmcnt(0)
	s_barrier
	s_and_saveexec_b64 s[40:41], s[6:7]
	s_cbranch_execz .LBB0_631
	v_readlane_b32 s6, v239, 63
	v_readlane_b32 s7, v241, 0
	v_mov_b32_e32 v3, 1
	s_nop 4
	global_atomic_add v4, v66, v3, s[6:7] offset:128 sc0
	buffer_inv sc1
	s_waitcnt vmcnt(0)
	v_readfirstlane_b32 s98, v4
	s_nop 3
	s_lshr_b32 s99, s98, 2
	s_and_b32 s98, s98, 3
	s_cmp_eq_u32 s98, 3
	s_cbranch_scc1 .Lgrp_last_1
	s_mov_b32 s100, 0

; __device__ __forceinline__ unsigned xb_ld(unsigned* p)              { return __hip_atomic_load(p, __ATOMIC_RELAXED, __HIP_MEMORY_SCOPE_AGENT); }
; #define XB_SPIN(cond, bar) do { unsigned _sp = 0; while (cond) { __builtin_amdgcn_s_sleep(1); \
;     if ((++_sp & 255u) == 0u) { if (xb_ld(&(bar)[XB_TMO])) break; if (_sp > XB_SPIN_CAP) { atomicAdd(&(bar)[XB_TMO], 1u); break; } } } } while (0)
; __device__ __forceinline__ void xcc_local_barrier(unsigned* bar2, unsigned x, unsigned nloc, unsigned* tmobar) {
;     ...
;         else XB_SPIN(xb_ld(&bar2[XB_XGEN(x)]) == gen, tmobar);
;         __builtin_amdgcn_fence(__ATOMIC_ACQUIRE, "agent");
;         asm volatile("s_waitcnt vmcnt(0)" ::: "memory");
;     }
;     __syncthreads();
.Lgrp_done_1:
	s_waitcnt vmcnt(0)
.LBB0_631:
	s_or_b64 exec, exec, s[40:41]
	s_barrier

; __device__ __forceinline__ unsigned xb_ld(unsigned* p)              { return __hip_atomic_load(p, __ATOMIC_RELAXED, __HIP_MEMORY_SCOPE_AGENT); }
; __device__ __forceinline__ unsigned xb_add(unsigned* p, unsigned v) { return __hip_atomic_fetch_add(p, v, __ATOMIC_RELAXED, __HIP_MEMORY_SCOPE_AGENT); }
; #define XB_SPIN(cond, bar) do { unsigned _sp = 0; while (cond) { __builtin_amdgcn_s_sleep(1); \
;     if ((++_sp & 255u) == 0u) { if (xb_ld(&(bar)[XB_TMO])) break; if (_sp > XB_SPIN_CAP) { atomicAdd(&(bar)[XB_TMO], 1u); break; } } } } while (0)
; __device__ __forceinline__ void xcc_local_barrier(unsigned* bar2, unsigned x, unsigned nloc, unsigned* tmobar) {
;     asm volatile("s_waitcnt vmcnt(0)" ::: "memory");
;     __syncthreads();
;     if (threadIdx.x == 0) {
;         const unsigned old = xb_add(&bar2[XB_XSUB(x)], 1u);
;         const unsigned gen = old / nloc;
;         if (old + 1u == (gen + 1u) * nloc) (void)xb_add(&bar2[XB_XGEN(x)], 1u);
;         else XB_SPIN(xb_ld(&bar2[XB_XGEN(x)]) == gen, tmobar);
.LBB0_721:
	s_and_b64 vcc, exec, s[44:45]
	s_cbranch_vccz .LBB0_741
	v_readlane_b32 s6, v238, 25
	s_nop 1
	v_mov_b32_e32 v2, s6
	ds_read_b32 v2, v2
	s_waitcnt vmcnt(0)
	v_readlane_b32 s6, v242, 38
	v_readlane_b32 s7, v242, 39
	s_waitcnt vmcnt(0) lgkmcnt(0)
	s_barrier
	s_and_saveexec_b64 s[44:45], s[6:7]
	s_cbranch_execz .LBB0_740
	v_readlane_b32 s6, v239, 63
	v_readlane_b32 s7, v241, 0
	v_mov_b32_e32 v3, 1
	s_nop 4
	global_atomic_add v4, v66, v3, s[6:7] offset:128 sc0
	buffer_inv sc1
	s_waitcnt vmcnt(0)
	v_readfirstlane_b32 s98, v4
	s_nop 3
	s_lshr_b32 s99, s98, 2
	s_and_b32 s98, s98, 3
	s_cmp_eq_u32 s98, 3
	s_cbranch_scc1 .Lgrp_last_2
	s_mov_b32 s100, 0

; __device__ __forceinline__ unsigned xb_ld(unsigned* p)              { return __hip_atomic_load(p, __ATOMIC_RELAXED, __HIP_MEMORY_SCOPE_AGENT); }
; #define XB_SPIN(cond, bar) do { unsigned _sp = 0; while (cond) { __builtin_amdgcn_s_sleep(1); \
;     if ((++_sp & 255u) == 0u) { if (xb_ld(&(bar)[XB_TMO])) break; if (_sp > XB_SPIN_CAP) { atomicAdd(&(bar)[XB_TMO], 1u); break; } } } } while (0)
; __device__ __forceinline__ void xcc_local_barrier(unsigned* bar2, unsigned x, unsigned nloc, unsigned* tmobar) {
;     ...
;         else XB_SPIN(xb_ld(&bar2[XB_XGEN(x)]) == gen, tmobar);
;         __builtin_amdgcn_fence(__ATOMIC_ACQUIRE, "agent");
;         asm volatile("s_waitcnt vmcnt(0)" ::: "memory");
;     }
;     __syncthreads();
.Lgrp_done_2:
	s_waitcnt vmcnt(0)
.LBB0_740:
	s_or_b64 exec, exec, s[44:45]
	s_barrier

; __device__ __forceinline__ unsigned xb_ld(unsigned* p)              { return __hip_atomic_load(p, __ATOMIC_RELAXED, __HIP_MEMORY_SCOPE_AGENT); }
; #define XB_SPIN(cond, bar) do { unsigned _sp = 0; while (cond) { __builtin_amdgcn_s_sleep(1); \
;     if ((++_sp & 255u) == 0u) { if (xb_ld(&(bar)[XB_TMO])) break; if (_sp > XB_SPIN_CAP) { atomicAdd(&(bar)[XB_TMO], 1u); break; } } } } while (0)
; __device__ __forceinline__ void xcc_local_barrier(unsigned* bar2, unsigned x, unsigned nloc, unsigned* tmobar) {
;     ...
;         else XB_SPIN(xb_ld(&bar2[XB_XGEN(x)]) == gen, tmobar);
;         __builtin_amdgcn_fence(__ATOMIC_ACQUIRE, "agent");
;         asm volatile("s_waitcnt vmcnt(0)" ::: "memory");
;     }
;     __syncthreads();
.Lgrp_done_3:
	s_waitcnt vmcnt(0)
.LBB0_893:
	s_or_b64 exec, exec, s[38:39]
	s_barrier

; __device__ __forceinline__ unsigned xb_ld(unsigned* p)              { return __hip_atomic_load(p, __ATOMIC_RELAXED, __HIP_MEMORY_SCOPE_AGENT); }
; __device__ __forceinline__ unsigned xb_add(unsigned* p, unsigned v) { return __hip_atomic_fetch_add(p, v, __ATOMIC_RELAXED, __HIP_MEMORY_SCOPE_AGENT); }
; #define XB_SPIN(cond, bar) do { unsigned _sp = 0; while (cond) { __builtin_amdgcn_s_sleep(1); \
;     if ((++_sp & 255u) == 0u) { if (xb_ld(&(bar)[XB_TMO])) break; if (_sp > XB_SPIN_CAP) { atomicAdd(&(bar)[XB_TMO], 1u); break; } } } } while (0)
; __device__ __forceinline__ void xcc_local_barrier(unsigned* bar2, unsigned x, unsigned nloc, unsigned* tmobar) {
;     asm volatile("s_waitcnt vmcnt(0)" ::: "memory");
;     __syncthreads();
;     if (threadIdx.x == 0) {
;         const unsigned old = xb_add(&bar2[XB_XSUB(x)], 1u);
;         const unsigned gen = old / nloc;
;         if (old + 1u == (gen + 1u) * nloc) (void)xb_add(&bar2[XB_XGEN(x)], 1u);
;         else XB_SPIN(xb_ld(&bar2[XB_XGEN(x)]) == gen, tmobar);
.LBB0_1044:
	s_and_b64 vcc, exec, s[36:37]
	s_cbranch_vccz .LBB0_1064
	v_readlane_b32 s6, v238, 25
	s_nop 1
	v_mov_b32_e32 v2, s6
	ds_read_b32 v2, v2
	s_waitcnt vmcnt(0)
	v_readlane_b32 s6, v242, 38
	v_readlane_b32 s7, v242, 39
	s_waitcnt vmcnt(0) lgkmcnt(0)
	s_barrier
	s_and_saveexec_b64 s[36:37], s[6:7]
	s_cbranch_execz .LBB0_1063
	v_readlane_b32 s6, v239, 63
	v_readlane_b32 s7, v241, 0
	v_mov_b32_e32 v3, 1
	s_nop 4
	global_atomic_add v4, v66, v3, s[6:7] offset:128 sc0
	buffer_inv sc1
	s_waitcnt vmcnt(0)
	v_readfirstlane_b32 s98, v4
	s_nop 3
	s_lshr_b32 s99, s98, 2
	s_and_b32 s98, s98, 3
	s_cmp_eq_u32 s98, 3
	s_cbranch_scc1 .Lgrp_last_4
	s_mov_b32 s100, 0

; __device__ __forceinline__ unsigned xb_ld(unsigned* p)              { return __hip_atomic_load(p, __ATOMIC_RELAXED, __HIP_MEMORY_SCOPE_AGENT); }
; #define XB_SPIN(cond, bar) do { unsigned _sp = 0; while (cond) { __builtin_amdgcn_s_sleep(1); \
;     if ((++_sp & 255u) == 0u) { if (xb_ld(&(bar)[XB_TMO])) break; if (_sp > XB_SPIN_CAP) { atomicAdd(&(bar)[XB_TMO], 1u); break; } } } } while (0)
; __device__ __forceinline__ void xcc_local_barrier(unsigned* bar2, unsigned x, unsigned nloc, unsigned* tmobar) {
;     ...
;         else XB_SPIN(xb_ld(&bar2[XB_XGEN(x)]) == gen, tmobar);
;         __builtin_amdgcn_fence(__ATOMIC_ACQUIRE, "agent");
;         asm volatile("s_waitcnt vmcnt(0)" ::: "memory");
;     }
;     __syncthreads();
.Lgrp_done_4:
	s_waitcnt vmcnt(0)
.LBB0_1063:
	s_or_b64 exec, exec, s[36:37]
	s_barrier

; __global__ void __launch_bounds__(NWAVES * 64, 2) mk_fwd(Args args) {
	.amdhsa_kernel _Z6mk_fwd4Args
		.amdhsa_group_segment_fixed_size 0
		.amdhsa_private_segment_fixed_size 0
		.amdhsa_kernarg_size 400
		.amdhsa_user_sgpr_count 2
		.amdhsa_user_sgpr_dispatch_ptr 0
		.amdhsa_user_sgpr_queue_ptr 0
		.amdhsa_user_sgpr_kernarg_segment_ptr 1
		.amdhsa_user_sgpr_dispatch_id 0
		.amdhsa_user_sgpr_kernarg_preload_length 0
		.amdhsa_user_sgpr_kernarg_preload_offset 0
		.amdhsa_user_sgpr_private_segment_size 0
		.amdhsa_uses_dynamic_stack 0
		.amdhsa_enable_private_segment 0
		.amdhsa_system_sgpr_workgroup_id_x 1
		.amdhsa_system_sgpr_workgroup_id_y 0
		.amdhsa_system_sgpr_workgroup_id_z 0
		.amdhsa_system_sgpr_workgroup_info 0
		.amdhsa_system_vgpr_workitem_id 0
		.amdhsa_next_free_vgpr 243
		.amdhsa_next_free_sgpr 102
		.amdhsa_accum_offset 244
		.amdhsa_reserve_vcc 1
		.amdhsa_float_round_mode_32 0
		.amdhsa_float_round_mode_16_64 0
		.amdhsa_float_denorm_mode_32 3
		.amdhsa_float_denorm_mode_16_64 3
		.amdhsa_dx10_clamp 1
		.amdhsa_ieee_mode 1
		.amdhsa_fp16_overflow 0
		.amdhsa_tg_split 0
		.amdhsa_exception_fp_ieee_invalid_op 0
		.amdhsa_exception_fp_denorm_src 0
		.amdhsa_exception_fp_ieee_div_zero 0
		.amdhsa_exception_fp_ieee_overflow 0
		.amdhsa_exception_fp_ieee_underflow 0
		.amdhsa_exception_fp_ieee_inexact 0
		.amdhsa_exception_int_div_zero 0
	.end_amdhsa_kernel

; #define LAS __attribute__((address_space(3)))
; __global__ void __launch_bounds__(NWAVES * 64, 2) mk_fwd(Args args) {
;     extern __shared__ __attribute__((aligned(16))) unsigned char lds_raw[];
;     LAS unsigned char* lds = (LAS unsigned char*)lds_raw;
amdhsa.kernels:
  - .agpr_count:     0
    .args:
      - .offset:         0
        .size:           144
        .value_kind:     by_value
      - .offset:         144
        .size:           4
        .value_kind:     hidden_block_count_x
      - .offset:         148
        .size:           4
        .value_kind:     hidden_block_count_y
      - .offset:         152
        .size:           4
        .value_kind:     hidden_block_count_z
      - .offset:         156
        .size:           2
        .value_kind:     hidden_group_size_x
      - .offset:         158
        .size:           2
        .value_kind:     hidden_group_size_y
      - .offset:         160
        .size:           2
        .value_kind:     hidden_group_size_z
      - .offset:         162
        .size:           2
        .value_kind:     hidden_remainder_x
      - .offset:         164
        .size:           2
        .value_kind:     hidden_remainder_y
      - .offset:         166
        .size:           2
        .value_kind:     hidden_remainder_z
      - .offset:         184
        .size:           8
        .value_kind:     hidden_global_offset_x
      - .offset:         192
        .size:           8
        .value_kind:     hidden_global_offset_y
      - .offset:         200
        .size:           8
        .value_kind:     hidden_global_offset_z
      - .offset:         208
        .size:           2
        .value_kind:     hidden_grid_dims
      - .offset:         264
        .size:           4
        .value_kind:     hidden_dynamic_lds_size
    .group_segment_fixed_size: 0
    .kernarg_segment_align: 8
    .kernarg_segment_size: 400
    .language:       OpenCL C
    .language_version:
      - 2
      - 0
    .max_flat_workgroup_size: 512
    .name:           _Z6mk_fwd4Args
    .private_segment_fixed_size: 0
    .sgpr_count:     108
    .sgpr_spill_count: 322
    .symbol:         _Z6mk_fwd4Args.kd
    .uniform_work_group_size: 1
    .uses_dynamic_stack: false
    .vgpr_count:     243
    .vgpr_spill_count: 0
    .wavefront_size: 64
